# hgrn pass 3: masked-score step reads issued ahead; segment fold double-buffered (next segment's 16 loads in flight while the current one is applied)
# baseline (speedup 1.0000x reference)
.LBB0_407:
	s_or_b64 exec, exec, s[22:23]
	v_mov_b32_e32 v16, 0
	s_andn2_b64 vcc, exec, s[20:21]
	v_mov_b32_e32 v17, 0
	v_mov_b32_e32 v18, 0
	v_mov_b32_e32 v19, 0
	v_mov_b32_e32 v12, 0
	v_mov_b32_e32 v13, 0
	v_mov_b32_e32 v14, 0
	v_mov_b32_e32 v15, 0
	v_mov_b32_e32 v24, 0
	v_mov_b32_e32 v25, 0
	v_mov_b32_e32 v26, 0
	v_mov_b32_e32 v27, 0
	v_mov_b32_e32 v20, 0
	v_mov_b32_e32 v21, 0
	v_mov_b32_e32 v22, 0
	v_mov_b32_e32 v23, 0
	v_mov_b32_e32 v32, 0
	v_mov_b32_e32 v33, 0
	v_mov_b32_e32 v34, 0
	v_mov_b32_e32 v35, 0
	v_mov_b32_e32 v28, 0
	v_mov_b32_e32 v29, 0
	v_mov_b32_e32 v30, 0
	v_mov_b32_e32 v31, 0
	v_mov_b32_e32 v36, 0
	v_mov_b32_e32 v37, 0
	v_mov_b32_e32 v38, 0
	v_mov_b32_e32 v39, 0
	v_mov_b32_e32 v40, 0
	v_mov_b32_e32 v41, 0
	v_mov_b32_e32 v42, 0
	v_mov_b32_e32 v43, 0
	s_cbranch_vccnz .LBB0_414
	s_lshl_b32 s20, s90, 2
	s_or_b32 s20, s20, s78
	s_or_b32 s20, s20, s92
	s_lshl_b32 s20, s20, 3
	s_or_b32 s20, s20, s91
	s_ashr_i32 s21, s20, 31
	s_lshl_b64 s[20:21], s[20:21], 16
	v_lshl_add_u64 v[36:37], v[56:57], 0, s[20:21]
	v_add_co_u32_e32 v20, vcc, 0x2000, v36
	s_cmp_lt_i32 s7, 1
	s_nop 0
	v_addc_co_u32_e32 v21, vcc, 0, v37, vcc
	global_load_dword v16, v[36:37], off
	global_load_dword v17, v[36:37], off offset:512
	global_load_dword v18, v[36:37], off offset:1024
	global_load_dword v19, v[36:37], off offset:1536
	global_load_dword v12, v[20:21], off
	global_load_dword v13, v[20:21], off offset:512
	global_load_dword v14, v[20:21], off offset:1024
	global_load_dword v15, v[20:21], off offset:1536
	v_add_co_u32_e32 v20, vcc, 0x4000, v36
	s_nop 1
	v_addc_co_u32_e32 v21, vcc, 0, v37, vcc
	v_add_co_u32_e32 v28, vcc, 0x6000, v36
	s_nop 1
	v_addc_co_u32_e32 v29, vcc, 0, v37, vcc
	global_load_dword v24, v[20:21], off
	global_load_dword v25, v[20:21], off offset:512
	global_load_dword v26, v[20:21], off offset:1024
	global_load_dword v27, v[20:21], off offset:1536
	s_nop 0
	global_load_dword v20, v[28:29], off
	global_load_dword v21, v[28:29], off offset:512
	global_load_dword v22, v[28:29], off offset:1024
	global_load_dword v23, v[28:29], off offset:1536
	v_add_co_u32_e32 v28, vcc, 0x8000, v36
	s_nop 1
	v_addc_co_u32_e32 v29, vcc, 0, v37, vcc
	v_add_co_u32_e32 v38, vcc, 0xa000, v36
	s_nop 1
	v_addc_co_u32_e32 v39, vcc, 0, v37, vcc
	v_add_co_u32_e32 v40, vcc, 0xc000, v36
	global_load_dword v32, v[28:29], off
	global_load_dword v33, v[28:29], off offset:512
	global_load_dword v34, v[28:29], off offset:1024
	global_load_dword v35, v[28:29], off offset:1536
	s_nop 0
	global_load_dword v28, v[38:39], off
	global_load_dword v29, v[38:39], off offset:512
	global_load_dword v30, v[38:39], off offset:1024
	global_load_dword v31, v[38:39], off offset:1536
	v_addc_co_u32_e32 v41, vcc, 0, v37, vcc
	v_add_co_u32_e32 v44, vcc, 0xe000, v36
	s_nop 1
	v_addc_co_u32_e32 v45, vcc, 0, v37, vcc
	global_load_dword v36, v[40:41], off
	global_load_dword v37, v[40:41], off offset:512
	global_load_dword v38, v[40:41], off offset:1024
	global_load_dword v39, v[40:41], off offset:1536
	s_nop 0
	global_load_dword v40, v[44:45], off
	global_load_dword v41, v[44:45], off offset:512
	global_load_dword v42, v[44:45], off offset:1024
	global_load_dword v43, v[44:45], off offset:1536
	s_cbranch_scc1 .LBB0_414
	s_mov_b32 s23, 0
	s_add_i32 s20, s6, s23
	s_ashr_i32 s21, s20, 31
	s_lshl_b64 vcc, s[20:21], 16
	v_lshl_add_u64 v[242:243], v[48:49], 0, vcc
	s_lshl_b64 vcc, s[20:21], 9
	v_lshl_add_u64 v[244:245], v[52:53], 0, vcc
	s_mov_b64 vcc, 0x2000
	global_load_dwordx4 v[166:169], v[244:245], off
	global_load_dwordx4 v[210:213], v[242:243], off
	v_lshl_add_u64 v[242:243], v[242:243], 0, vcc
	global_load_dwordx4 v[170:173], v[244:245], off offset:64
	global_load_dwordx4 v[214:217], v[242:243], off
	v_lshl_add_u64 v[242:243], v[242:243], 0, vcc
	global_load_dwordx4 v[174:177], v[244:245], off offset:128
	global_load_dwordx4 v[218:221], v[242:243], off
	v_lshl_add_u64 v[242:243], v[242:243], 0, vcc
	global_load_dwordx4 v[178:181], v[244:245], off offset:192
	global_load_dwordx4 v[222:225], v[242:243], off
	v_lshl_add_u64 v[242:243], v[242:243], 0, vcc
	global_load_dwordx4 v[182:185], v[244:245], off offset:256
	global_load_dwordx4 v[226:229], v[242:243], off
	v_lshl_add_u64 v[242:243], v[242:243], 0, vcc
	global_load_dwordx4 v[186:189], v[244:245], off offset:320
	global_load_dwordx4 v[230:233], v[242:243], off
	v_lshl_add_u64 v[242:243], v[242:243], 0, vcc
	global_load_dwordx4 v[190:193], v[244:245], off offset:384
	global_load_dwordx4 v[234:237], v[242:243], off
	v_lshl_add_u64 v[242:243], v[242:243], 0, vcc
	global_load_dwordx4 v[206:209], v[244:245], off offset:448
	global_load_dwordx4 v[238:241], v[242:243], off
	s_waitcnt vmcnt(16)
.Lfold_loop:
	s_add_i32 s23, s23, 1
	s_cmp_ge_u32 s23, s7
	s_cbranch_scc1 .Lfold_last_a
	s_add_i32 s20, s6, s23
	s_ashr_i32 s21, s20, 31
	s_lshl_b64 vcc, s[20:21], 16
	v_lshl_add_u64 v[242:243], v[48:49], 0, vcc
	s_lshl_b64 vcc, s[20:21], 9
	v_lshl_add_u64 v[244:245], v[52:53], 0, vcc
	s_mov_b64 vcc, 0x2000
	global_load_dwordx4 v[100:103], v[244:245], off
	global_load_dwordx4 v[132:135], v[242:243], off
	v_lshl_add_u64 v[242:243], v[242:243], 0, vcc
	global_load_dwordx4 v[104:107], v[244:245], off offset:64
	global_load_dwordx4 v[136:139], v[242:243], off
	v_lshl_add_u64 v[242:243], v[242:243], 0, vcc
	global_load_dwordx4 v[108:111], v[244:245], off offset:128
	global_load_dwordx4 v[140:143], v[242:243], off
	v_lshl_add_u64 v[242:243], v[242:243], 0, vcc
	global_load_dwordx4 v[112:115], v[244:245], off offset:192
	global_load_dwordx4 v[144:147], v[242:243], off
	v_lshl_add_u64 v[242:243], v[242:243], 0, vcc
	global_load_dwordx4 v[116:119], v[244:245], off offset:256
	global_load_dwordx4 v[148:151], v[242:243], off
	v_lshl_add_u64 v[242:243], v[242:243], 0, vcc
	global_load_dwordx4 v[120:123], v[244:245], off offset:320
	global_load_dwordx4 v[44:47], v[242:243], off
	v_lshl_add_u64 v[242:243], v[242:243], 0, vcc
	global_load_dwordx4 v[124:127], v[244:245], off offset:384
	global_load_dwordx4 v[60:63], v[242:243], off
	v_lshl_add_u64 v[242:243], v[242:243], 0, vcc
	global_load_dwordx4 v[128:131], v[244:245], off offset:448
	global_load_dwordx4 v[162:165], v[242:243], off
	s_waitcnt vmcnt(30)
	v_pk_fma_f32 v[16:17], v[16:17], v[166:167], v[210:211]
	v_pk_fma_f32 v[18:19], v[18:19], v[168:169], v[212:213]
	s_waitcnt vmcnt(28)
	v_pk_fma_f32 v[12:13], v[12:13], v[170:171], v[214:215]
	v_pk_fma_f32 v[14:15], v[14:15], v[172:173], v[216:217]
	s_waitcnt vmcnt(26)
	v_pk_fma_f32 v[24:25], v[24:25], v[174:175], v[218:219]
	v_pk_fma_f32 v[26:27], v[26:27], v[176:177], v[220:221]
	s_waitcnt vmcnt(24)
	v_pk_fma_f32 v[20:21], v[20:21], v[178:179], v[222:223]
	v_pk_fma_f32 v[22:23], v[22:23], v[180:181], v[224:225]
	s_waitcnt vmcnt(22)
	v_pk_fma_f32 v[32:33], v[32:33], v[182:183], v[226:227]
	v_pk_fma_f32 v[34:35], v[34:35], v[184:185], v[228:229]
	s_waitcnt vmcnt(20)
	v_pk_fma_f32 v[28:29], v[28:29], v[186:187], v[230:231]
	v_pk_fma_f32 v[30:31], v[30:31], v[188:189], v[232:233]
	s_waitcnt vmcnt(18)
	v_pk_fma_f32 v[36:37], v[36:37], v[190:191], v[234:235]
	v_pk_fma_f32 v[38:39], v[38:39], v[192:193], v[236:237]
	s_waitcnt vmcnt(16)
	v_pk_fma_f32 v[40:41], v[40:41], v[206:207], v[238:239]
	v_pk_fma_f32 v[42:43], v[42:43], v[208:209], v[240:241]
	s_add_i32 s23, s23, 1
	s_cmp_ge_u32 s23, s7
	s_cbranch_scc1 .Lfold_last_b
	s_add_i32 s20, s6, s23
	s_ashr_i32 s21, s20, 31
	s_lshl_b64 vcc, s[20:21], 16
	v_lshl_add_u64 v[242:243], v[48:49], 0, vcc
	s_lshl_b64 vcc, s[20:21], 9
	v_lshl_add_u64 v[244:245], v[52:53], 0, vcc
	s_mov_b64 vcc, 0x2000
	global_load_dwordx4 v[166:169], v[244:245], off
	global_load_dwordx4 v[210:213], v[242:243], off
	v_lshl_add_u64 v[242:243], v[242:243], 0, vcc
	global_load_dwordx4 v[170:173], v[244:245], off offset:64
	global_load_dwordx4 v[214:217], v[242:243], off
	v_lshl_add_u64 v[242:243], v[242:243], 0, vcc
	global_load_dwordx4 v[174:177], v[244:245], off offset:128
	global_load_dwordx4 v[218:221], v[242:243], off
	v_lshl_add_u64 v[242:243], v[242:243], 0, vcc
	global_load_dwordx4 v[178:181], v[244:245], off offset:192
	global_load_dwordx4 v[222:225], v[242:243], off
	v_lshl_add_u64 v[242:243], v[242:243], 0, vcc
	global_load_dwordx4 v[182:185], v[244:245], off offset:256
	global_load_dwordx4 v[226:229], v[242:243], off
	v_lshl_add_u64 v[242:243], v[242:243], 0, vcc
	global_load_dwordx4 v[186:189], v[244:245], off offset:320
	global_load_dwordx4 v[230:233], v[242:243], off
	v_lshl_add_u64 v[242:243], v[242:243], 0, vcc
	global_load_dwordx4 v[190:193], v[244:245], off offset:384
	global_load_dwordx4 v[234:237], v[242:243], off
	v_lshl_add_u64 v[242:243], v[242:243], 0, vcc
	global_load_dwordx4 v[206:209], v[244:245], off offset:448
	global_load_dwordx4 v[238:241], v[242:243], off
	s_waitcnt vmcnt(30)
	v_pk_fma_f32 v[16:17], v[16:17], v[100:101], v[132:133]
	v_pk_fma_f32 v[18:19], v[18:19], v[102:103], v[134:135]
	s_waitcnt vmcnt(28)
	v_pk_fma_f32 v[12:13], v[12:13], v[104:105], v[136:137]
	v_pk_fma_f32 v[14:15], v[14:15], v[106:107], v[138:139]
	s_waitcnt vmcnt(26)
	v_pk_fma_f32 v[24:25], v[24:25], v[108:109], v[140:141]
	v_pk_fma_f32 v[26:27], v[26:27], v[110:111], v[142:143]
	s_waitcnt vmcnt(24)
	v_pk_fma_f32 v[20:21], v[20:21], v[112:113], v[144:145]
	v_pk_fma_f32 v[22:23], v[22:23], v[114:115], v[146:147]
	s_waitcnt vmcnt(22)
	v_pk_fma_f32 v[32:33], v[32:33], v[116:117], v[148:149]
	v_pk_fma_f32 v[34:35], v[34:35], v[118:119], v[150:151]
	s_waitcnt vmcnt(20)
	v_pk_fma_f32 v[28:29], v[28:29], v[120:121], v[44:45]
	v_pk_fma_f32 v[30:31], v[30:31], v[122:123], v[46:47]
	s_waitcnt vmcnt(18)
	v_pk_fma_f32 v[36:37], v[36:37], v[124:125], v[60:61]
	v_pk_fma_f32 v[38:39], v[38:39], v[126:127], v[62:63]
	s_waitcnt vmcnt(16)
	v_pk_fma_f32 v[40:41], v[40:41], v[128:129], v[162:163]
	v_pk_fma_f32 v[42:43], v[42:43], v[130:131], v[164:165]
	s_branch .Lfold_loop
.Lfold_last_a:
	s_waitcnt vmcnt(14)
	v_pk_fma_f32 v[16:17], v[16:17], v[166:167], v[210:211]
	v_pk_fma_f32 v[18:19], v[18:19], v[168:169], v[212:213]
	s_waitcnt vmcnt(12)
	v_pk_fma_f32 v[12:13], v[12:13], v[170:171], v[214:215]
	v_pk_fma_f32 v[14:15], v[14:15], v[172:173], v[216:217]
	s_waitcnt vmcnt(10)
	v_pk_fma_f32 v[24:25], v[24:25], v[174:175], v[218:219]
	v_pk_fma_f32 v[26:27], v[26:27], v[176:177], v[220:221]
	s_waitcnt vmcnt(8)
	v_pk_fma_f32 v[20:21], v[20:21], v[178:179], v[222:223]
	v_pk_fma_f32 v[22:23], v[22:23], v[180:181], v[224:225]
	s_waitcnt vmcnt(6)
	v_pk_fma_f32 v[32:33], v[32:33], v[182:183], v[226:227]
	v_pk_fma_f32 v[34:35], v[34:35], v[184:185], v[228:229]
	s_waitcnt vmcnt(4)
	v_pk_fma_f32 v[28:29], v[28:29], v[186:187], v[230:231]
	v_pk_fma_f32 v[30:31], v[30:31], v[188:189], v[232:233]
	s_waitcnt vmcnt(2)
	v_pk_fma_f32 v[36:37], v[36:37], v[190:191], v[234:235]
	v_pk_fma_f32 v[38:39], v[38:39], v[192:193], v[236:237]
	s_waitcnt vmcnt(0)
	v_pk_fma_f32 v[40:41], v[40:41], v[206:207], v[238:239]
	v_pk_fma_f32 v[42:43], v[42:43], v[208:209], v[240:241]
	s_branch .Lfold_done
.Lfold_last_b:
	s_waitcnt vmcnt(14)
	v_pk_fma_f32 v[16:17], v[16:17], v[100:101], v[132:133]
	v_pk_fma_f32 v[18:19], v[18:19], v[102:103], v[134:135]
	s_waitcnt vmcnt(12)
	v_pk_fma_f32 v[12:13], v[12:13], v[104:105], v[136:137]
	v_pk_fma_f32 v[14:15], v[14:15], v[106:107], v[138:139]
	s_waitcnt vmcnt(10)
	v_pk_fma_f32 v[24:25], v[24:25], v[108:109], v[140:141]
	v_pk_fma_f32 v[26:27], v[26:27], v[110:111], v[142:143]
	s_waitcnt vmcnt(8)
	v_pk_fma_f32 v[20:21], v[20:21], v[112:113], v[144:145]
	v_pk_fma_f32 v[22:23], v[22:23], v[114:115], v[146:147]
	s_waitcnt vmcnt(6)
	v_pk_fma_f32 v[32:33], v[32:33], v[116:117], v[148:149]
	v_pk_fma_f32 v[34:35], v[34:35], v[118:119], v[150:151]
	s_waitcnt vmcnt(4)
	v_pk_fma_f32 v[28:29], v[28:29], v[120:121], v[44:45]
	v_pk_fma_f32 v[30:31], v[30:31], v[122:123], v[46:47]
	s_waitcnt vmcnt(2)
	v_pk_fma_f32 v[36:37], v[36:37], v[124:125], v[60:61]
	v_pk_fma_f32 v[38:39], v[38:39], v[126:127], v[62:63]
	s_waitcnt vmcnt(0)
	v_pk_fma_f32 v[40:41], v[40:41], v[128:129], v[162:163]
	v_pk_fma_f32 v[42:43], v[42:43], v[130:131], v[164:165]
.Lfold_done:
.LBB0_414:
	s_mul_i32 s6, s92, 0x1800000
	s_add_u32 s22, s15, s6
	s_addc_u32 s23, s14, 0
	s_lshl_b32 s20, s5, 1
	s_add_u32 vcc_lo, s22, s20
	s_mov_b32 s21, s31
	s_addc_u32 vcc_hi, s23, 0
	v_add_u32_e32 v44, s94, v92
	s_mov_b32 s6, 1
	v_lshl_add_u64 v[60:61], v[54:55], 0, s[20:21]
	v_lshl_add_u64 v[62:63], vcc, 0, v[152:153]
	s_sub_i32 s5, 0, s95
	v_add_u32_e32 v99, s4, v91
	v_subrev_u32_e32 v100, s4, v44
	s_waitcnt lgkmcnt(0)
	s_barrier
	s_branch .LBB0_416

.LBB0_422:
	s_waitcnt lgkmcnt(0)
	s_barrier
	s_andn2_b64 vcc, exec, s[16:17]
	s_cbranch_vccnz .LBB0_415
	ds_read_b128 v[166:169], v74 offset:49152
	ds_read_b128 v[170:173], v75 offset:57856
	ds_read_b128 v[174:177], v74 offset:49216
	ds_read_b128 v[178:181], v75 offset:57920
	ds_read_b128 v[182:185], v74 offset:49280
	ds_read_b128 v[186:189], v75 offset:57984
	ds_read_b128 v[190:193], v74 offset:49344
	ds_read_b128 v[206:209], v75 offset:58048
	s_waitcnt lgkmcnt(6)
	v_mfma_f32_16x16x32_bf16 v[44:47], v[166:169], v[170:173], 0
	s_waitcnt lgkmcnt(4)
	v_mfma_f32_16x16x32_bf16 v[44:47], v[174:177], v[178:181], v[44:47]
	s_waitcnt lgkmcnt(2)
	v_mfma_f32_16x16x32_bf16 v[44:47], v[182:185], v[186:189], v[44:47]
	s_waitcnt lgkmcnt(0)
	v_mfma_f32_16x16x32_bf16 v[44:47], v[190:193], v[206:209], v[44:47]
	s_nop 7
	v_cndmask_b32_e64 v44, v44, 0, s[54:55]
	v_cvt_pk_bf16_f32 v44, v44, v153
	ds_write_b16 v95, v44
	v_cndmask_b32_e64 v44, v45, 0, s[56:57]
	v_cvt_pk_bf16_f32 v44, v44, v153
	ds_write_b16 v95, v44 offset:80
	v_cndmask_b32_e64 v44, v46, 0, s[58:59]
	v_cvt_pk_bf16_f32 v44, v44, v153
	ds_write_b16 v95, v44 offset:160
	v_cndmask_b32_e64 v44, v47, 0, s[60:61]
	v_cvt_pk_bf16_f32 v44, v44, v153
	ds_write_b16 v95, v44 offset:240
	s_branch .LBB0_415
